# hand-written software-pipelined scan loop (W one chunk ahead, permuted LDS layout, b128 frag reads, exp precompute)
# speedup vs baseline: 1.2292x; 1.2292x over previous
; __device__ __forceinline__ void phase_scan(KP kp_){ asm volatile("" : "+s"(kp_)); const Params p=load_params(kp_);
;     ...
;   int tid=ftid, lane=tid&63, wv=tid>>6, r=lane&15, kg=lane>>4;
;   for (int item=blockIdx.x; item<32; item+=gridDim.x){
;     int d=item&1, h=(item>>1)&7, b=item>>4;
;     char* tabase = d ? (p.ws+OFF_TAB) : (char*)p.out;
;     f32x4 Sacc[8];
;     _Pragma("unroll") for (int i=0;i<8;++i) Sacc[i]=f32x4{0.f,0.f,0.f,0.f};
;     u32x4 pq0A,pq1A,pk0A,pk1A,pv0A,pv1A,pt0A,pt1A,pt2A; float pgA;
;     u32x4 pq0B,pq1B,pk0B,pk1B,pv0B,pv1B,pt0B,pt1B,pt2B; float pgB;
;     ...
;     __syncthreads();
;     PREFETCH(A,0); FILL(A);
;     __syncthreads();
;     ...
;       const float* gcs=(const float*)(smem+SGC);
;       float gl = d ? gcs[0] : gcs[63];
;       float gam=__expf(gl);
;       f32x4 vs[4];
;       _Pragma("unroll") for (int t=0;t<4;++t){ float4 g4=*(const float4*)(gcs+t*16+kg*4);
;         oacc[t][0]*=__expf(g4.x); oacc[t][1]*=__expf(g4.y); oacc[t][2]*=__expf(g4.z); oacc[t][3]*=__expf(g4.w);
;         vs[t][0]=vn[t][0]*__expf(gl-g4.x); vs[t][1]=vn[t][1]*__expf(gl-g4.y); vs[t][2]=vn[t][2]*__expf(gl-g4.z); vs[t][3]=vn[t][3]*__expf(gl-g4.w); }
.LBB0_919:
	s_and_b64 vcc, exec, s[0:1]
	s_cbranch_vccz .LBB0_960
	s_mov_b64 exec, -1
	s_load_dwordx4 s[12:15], s[78:79], 0xd8
	s_and_b32 s2, s75, 1
	s_bfe_u32 s0, s75, 0x30001
	s_lshr_b32 s1, s75, 4
	v_and_b32_e32 v153, 63, v154
	v_and_b32_e32 v240, 15, v153
	v_lshrrev_b32_e32 v241, 4, v153
	v_lshrrev_b32_e32 v242, 6, v154
	v_mul_u32_u24_e32 v133, 0x110, v240
	v_readfirstlane_b32 s3, v242
	v_lshl_add_u32 v133, v241, 4, v133
	v_mul_u32_u24_e32 v134, 0x90, v240
	v_lshl_add_u32 v134, v241, 4, v134
	v_mul_u32_u24_e32 v243, 0x900, v242
	v_add_u32_e32 v135, v134, v243
	v_lshrrev_b32_e32 v243, 1, v242
	v_and_b32_e32 v244, 1, v242
	v_lshl_add_u32 v136, v243, 6, v133
	v_lshl_add_u32 v136, v244, 3, v136
	v_add_u32_e32 v204, 0x19000, v136
	v_add_u32_e32 v205, 0x1d400, v136
	v_add_u32_e32 v200, 0x19000, v133
	v_add_u32_e32 v201, 0x1d400, v133
	v_add_u32_e32 v202, 0x10000, v134
	v_add_u32_e32 v203, 0x10000, v135
	v_lshlrev_b32_e32 v137, 4, v241
	v_lshrrev_b32_e32 v243, 4, v154
	v_and_b32_e32 v244, 15, v154
	v_lshrrev_b32_e32 v245, 2, v244
	v_lshlrev_b32_e32 v245, 6, v245
	v_and_b32_e32 v246, 1, v244
	v_lshl_add_u32 v245, v246, 5, v245
	v_bfe_u32 v246, v244, 1, 1
	v_lshl_add_u32 v245, v246, 3, v245
	v_mul_u32_u24_e32 v246, 0x110, v243
	v_add_u32_e32 v138, v246, v245
	v_add_u32_e32 v139, 0x2200, v138
	v_mul_u32_u24_e32 v149, 0x1800, v243
	v_lshl_add_u32 v149, v244, 4, v149
	v_lshrrev_b32_e32 v243, 3, v154
	v_and_b32_e32 v244, 7, v154
	v_lshrrev_b32_e32 v245, 2, v244
	v_lshlrev_b32_e32 v245, 6, v245
	v_and_b32_e32 v246, 1, v244
	v_lshl_add_u32 v245, v246, 5, v245
	v_bfe_u32 v246, v244, 1, 1
	v_lshl_add_u32 v245, v246, 3, v245
	v_mul_u32_u24_e32 v246, 0x90, v243
	v_add_u32_e32 v247, v246, v245
	v_lshl_add_u32 v146, v244, 4, v246
	v_add_u32_e32 v146, 0x10000, v146
	v_add_u32_e32 v140, 0x4400, v247
	v_add_u32_e32 v141, 0x6800, v247
	v_add_u32_e32 v142, 0x8c00, v247
	v_add_u32_e32 v143, 0xb000, v247
	v_add_u32_e32 v144, 0x14800, v247
	v_add_u32_e32 v145, 0xd400, v247
	v_lshlrev_b32_e32 v147, 2, v154
	v_lshlrev_b32_e32 v148, 4, v154
	v_lshlrev_b32_e32 v156, 10, v241
	v_lshl_add_u32 v156, v242, 5, v156
	v_lshl_add_u32 v156, v240, 1, v156
	v_add_u32_e32 v157, 0x1000, v156
	v_add_u32_e32 v158, 0x2000, v156
	v_add_u32_e32 v159, 0x3000, v156
	v_mov_b32_e32 v0, 0
	v_mov_b32_e32 v1, 0
	v_mov_b32_e32 v2, 0
	v_mov_b32_e32 v3, 0
	v_mov_b32_e32 v4, 0
	v_mov_b32_e32 v5, 0
	v_mov_b32_e32 v6, 0
	v_mov_b32_e32 v7, 0
	v_mov_b32_e32 v8, 0
	v_mov_b32_e32 v9, 0
	v_mov_b32_e32 v10, 0
	v_mov_b32_e32 v11, 0
	v_mov_b32_e32 v12, 0
	v_mov_b32_e32 v13, 0
	v_mov_b32_e32 v14, 0
	v_mov_b32_e32 v15, 0
	v_mov_b32_e32 v16, 0
	v_mov_b32_e32 v17, 0
	v_mov_b32_e32 v18, 0
	v_mov_b32_e32 v19, 0
	v_mov_b32_e32 v20, 0
	v_mov_b32_e32 v21, 0
	v_mov_b32_e32 v22, 0
	v_mov_b32_e32 v23, 0
	v_mov_b32_e32 v24, 0
	v_mov_b32_e32 v25, 0
	v_mov_b32_e32 v26, 0
	v_mov_b32_e32 v27, 0
	v_mov_b32_e32 v28, 0
	v_mov_b32_e32 v29, 0
	v_mov_b32_e32 v30, 0
	v_mov_b32_e32 v31, 0
	s_waitcnt lgkmcnt(0)
	s_add_u32 s16, s14, 0xa5bd000
	s_addc_u32 s17, s15, 0
	s_cmp_eq_u32 s2, 0
	s_cselect_b32 s8, s12, s16
	s_cselect_b32 s9, s13, s17
	s_cselect_b32 s11, 63, 0
	s_lshl_b32 s16, s1, 3
	s_add_u32 s16, s16, s0
	s_mul_i32 s16, s16, 0x339000
	s_add_u32 s8, s8, s16
	s_addc_u32 s9, s9, 0
	s_lshl_b32 s16, s1, 5
	s_add_u32 s16, s16, s0
	s_mul_i32 s16, s16, 0xc000
	s_add_u32 s4, s14, 0x3fbd000
	s_addc_u32 s5, s15, 0
	s_add_u32 s4, s4, s16
	s_addc_u32 s5, s5, 0
	s_mul_i32 s16, s1, 0x3000000
	s_lshl_b32 s17, s0, 8
	s_add_u32 s16, s16, s17
	s_add_u32 s6, s14, 0x413d000
	s_addc_u32 s7, s15, 0
	s_add_u32 s6, s6, s16
	s_addc_u32 s7, s7, 0
	s_mov_b32 s12, 0
	s_sub_u32 s13, 3, s12
	s_sub_u32 s0, 0x87, s12
	s_cmp_lt_u32 s12, 4
	s_cselect_b32 s13, s13, s0
	s_cselect_b32 s18, 1, 0
	s_cmp_eq_u32 s2, 0
	s_cselect_b32 s12, s12, s13
	s_mul_i32 s13, s12, 0x60000
	s_cmp_eq_u32 s18, 1
	s_cselect_b32 s14, s4, s6
	s_cselect_b32 s15, s5, s7
	s_add_u32 s14, s14, s13
	s_addc_u32 s15, s15, 0
	s_mul_i32 s13, s12, 0x6400
	s_add_u32 s16, s8, s13
	s_addc_u32 s17, s9, 0
	s_mul_i32 s12, s18, 0x3800
	s_add_u32 s12, s12, 0x800
	s_mul_i32 s13, s18, 0x2e000
	s_sub_u32 s13, 0x30000, s13
	s_cmp_eq_u32 s18, 1
	s_cselect_b64 vcc, -1, 0
	s_add_u32 s36, s14, s12
	s_addc_u32 s37, s15, 0
	s_add_u32 s40, s36, s12
	s_addc_u32 s41, s37, 0
	s_add_u32 s38, s36, s13
	s_addc_u32 s39, s37, 0
	s_add_u32 s42, s40, s13
	s_addc_u32 s43, s41, 0
	s_add_u32 s46, s16, 0x2000
	s_addc_u32 s47, s17, 0
	v_cndmask_b32_e32 v151, v149, v148, vcc
	s_mov_b32 s19, s18
	s_mov_b64 s[20:21], s[14:15]
	s_mov_b64 s[22:23], s[16:17]
	s_mul_i32 s13, s19, 0x2e000
	s_sub_u32 s13, 0x30000, s13
	s_cmp_eq_u32 s19, 1
	s_cselect_b64 vcc, -1, 0
	s_add_u32 s28, s20, s13
	s_addc_u32 s29, s21, 0
	s_add_u32 s30, s22, 0x4000
	s_addc_u32 s31, s23, 0
	s_add_u32 s34, s22, 0x6000
	s_addc_u32 s35, s23, 0
	v_cndmask_b32_e32 v150, v149, v148, vcc
	s_mov_b64 s[24:25], s[22:23]
	s_barrier
	global_load_dwordx4 v[96:99], v150, s[20:21]
	global_load_dwordx4 v[100:103], v150, s[28:29]
	global_load_dwordx4 v[128:131], v148, s[30:31]
	s_cmp_lg_u32 s3, 0
	s_cbranch_scc1 .Lmy_sc_nog0
	global_load_dword v132, v147, s[34:35]
.Lmy_sc_nog0:
	global_load_dwordx4 v[104:107], v151, s[36:37]
	global_load_dwordx4 v[108:111], v151, s[38:39]
	global_load_dwordx4 v[112:115], v151, s[40:41]
	global_load_dwordx4 v[116:119], v151, s[42:43]
	global_load_dwordx4 v[120:123], v148, s[16:17]
	global_load_dwordx4 v[124:127], v148, s[46:47]
	s_waitcnt vmcnt(0)
	ds_write2_b64 v138, v[96:97], v[98:99] offset1:2
	ds_write2_b64 v139, v[100:101], v[102:103] offset1:2
	ds_write2_b64 v145, v[128:129], v[130:131] offset1:2
	s_cmp_lg_u32 s3, 0
	s_cbranch_scc1 .Lmy_sc_noe1
	v_mul_f32_e32 v240, 0x3fb8aa3b, v132
	v_readlane_b32 s12, v132, s11
	s_nop 0
	v_exp_f32_e32 v240, v240
	s_nop 1
	v_sub_f32_e32 v241, s12, v132
	v_mov_b32_e32 v242, s12
	s_nop 0
	v_mul_f32_e32 v241, 0x3fb8aa3b, v241
	v_mul_f32_e32 v242, 0x3fb8aa3b, v242
	s_nop 0
	v_exp_f32_e32 v241, v241
	v_exp_f32_e32 v242, v242
	s_nop 1
	ds_write_b32 v147, v240 offset:63488
	ds_write_b32 v147, v241 offset:63744
	ds_write_b32 v147, v242 offset:64000
; __device__ __forceinline__ unsigned pack2(float a, float b){ f32x2_t v={a,b}; bf16x2_t r=__builtin_convertvector(v,bf16x2_t); return __builtin_bit_cast(unsigned,r); }
; #define MF(a,b,c) __builtin_amdgcn_mfma_f32_16x16x32_bf16(a,b,c,0,0,0)
; __device__ __forceinline__ void phase_scan(KP kp_){ asm volatile("" : "+s"(kp_)); const Params p=load_params(kp_);
;     ...
;     __syncthreads();
;     PREFETCH(A,0); FILL(A);
;     __syncthreads();
;     for (int s2=0; s2<132; s2+=2){
;       { const int s=s2;
;         if (s+1<132) PREFETCH(A,s+1);
;       f32x4 wacc[4], vn[4];
;       _Pragma("unroll") for (int i=0;i<4;++i){ wacc[i]=f32x4{0.f,0.f,0.f,0.f}; vn[i]=f32x4{0.f,0.f,0.f,0.f}; }
;       _Pragma("unroll") for (int ks=0;ks<2;++ks){ int kb=(ks*32+kg*8)*2;
;         bf16x8 A=lds128(SKT+(wv*16+r)*144+kb);
;         bf16x8 Bv=lds128(SVT+(wv*16+r)*144+kb);
;         _Pragma("unroll") for (int t=0;t<4;++t){
;           wacc[t]=MF(A, lds128(STW+(t*16+r)*144+kb), wacc[t]);
;           vn[t]=MF(lds128(STU+(t*16+r)*144+kb), Bv, vn[t]); } }
;       _Pragma("unroll") for (int t=0;t<4;++t){ uint2 pk2; pk2.x=pack2(-wacc[t][0],-wacc[t][1]); pk2.y=pack2(-wacc[t][2],-wacc[t][3]);
;         *(uint2*)(smem+SWB+(t*16+r)*272+(wv*16+kg*4)*2)=pk2; }
.Lmy_sc_noe1:
	ds_write2_b64 v140, v[104:105], v[106:107] offset1:2
	ds_write2_b64 v141, v[108:109], v[110:111] offset1:2
	ds_write_b128 v146, v[112:115] offset:0
	ds_write_b128 v146, v[116:119] offset:9216
	ds_write2_b64 v144, v[120:121], v[122:123] offset1:2
	ds_write_b128 v146, v[124:127] offset:27648
	s_waitcnt lgkmcnt(0)
	s_barrier
	s_mov_b32 s12, 1
	s_sub_u32 s13, 3, s12
	s_sub_u32 s0, 0x87, s12
	s_cmp_lt_u32 s12, 4
	s_cselect_b32 s13, s13, s0
	s_cselect_b32 s18, 1, 0
	s_cmp_eq_u32 s2, 0
	s_cselect_b32 s12, s12, s13
	s_mul_i32 s13, s12, 0x60000
	s_cmp_eq_u32 s18, 1
	s_cselect_b32 s14, s4, s6
	s_cselect_b32 s15, s5, s7
	s_add_u32 s14, s14, s13
	s_addc_u32 s15, s15, 0
	s_mul_i32 s13, s12, 0x6400
	s_add_u32 s16, s8, s13
	s_addc_u32 s17, s9, 0
	s_mul_i32 s12, s18, 0x3800
	s_add_u32 s12, s12, 0x800
	s_mul_i32 s13, s18, 0x2e000
	s_sub_u32 s13, 0x30000, s13
	s_cmp_eq_u32 s18, 1
	s_cselect_b64 vcc, -1, 0
	s_add_u32 s36, s14, s12
	s_addc_u32 s37, s15, 0
	s_add_u32 s40, s36, s12
	s_addc_u32 s41, s37, 0
	s_add_u32 s38, s36, s13
	s_addc_u32 s39, s37, 0
	s_add_u32 s42, s40, s13
	s_addc_u32 s43, s41, 0
	s_add_u32 s46, s16, 0x2000
	s_addc_u32 s47, s17, 0
	v_cndmask_b32_e32 v151, v149, v148, vcc
	global_load_dwordx4 v[104:107], v151, s[36:37]
	global_load_dwordx4 v[108:111], v151, s[38:39]
	global_load_dwordx4 v[112:115], v151, s[40:41]
	global_load_dwordx4 v[116:119], v151, s[42:43]
	global_load_dwordx4 v[120:123], v148, s[16:17]
	global_load_dwordx4 v[124:127], v148, s[46:47]
	ds_read_b128 v[208:211], v135 offset:17408
	ds_read_b128 v[212:215], v135 offset:17472
	ds_read_b128 v[216:219], v203 offset:0
	ds_read_b128 v[220:223], v203 offset:64
	ds_read_b128 v[160:163], v202 offset:18432
	ds_read_b128 v[164:167], v202 offset:20736
	ds_read_b128 v[168:171], v202 offset:23040
	ds_read_b128 v[172:175], v202 offset:25344
	ds_read_b128 v[176:179], v202 offset:18496
	ds_read_b128 v[180:183], v202 offset:20800
	ds_read_b128 v[184:187], v202 offset:23104
	ds_read_b128 v[188:191], v202 offset:25408
	s_waitcnt lgkmcnt(7)
	v_mfma_f32_16x16x32_bf16 v[32:35], v[208:211], v[160:163], 0
	s_waitcnt lgkmcnt(6)
	v_mfma_f32_16x16x32_bf16 v[36:39], v[208:211], v[164:167], 0
	s_waitcnt lgkmcnt(5)
	v_mfma_f32_16x16x32_bf16 v[40:43], v[208:211], v[168:171], 0
	s_waitcnt lgkmcnt(4)
	v_mfma_f32_16x16x32_bf16 v[44:47], v[208:211], v[172:175], 0
	s_waitcnt lgkmcnt(3)
	v_mfma_f32_16x16x32_bf16 v[32:35], v[212:215], v[176:179], v[32:35]
	s_waitcnt lgkmcnt(2)
	v_mfma_f32_16x16x32_bf16 v[36:39], v[212:215], v[180:183], v[36:39]
	s_waitcnt lgkmcnt(1)
	v_mfma_f32_16x16x32_bf16 v[40:43], v[212:215], v[184:187], v[40:43]
	s_waitcnt lgkmcnt(0)
	v_mfma_f32_16x16x32_bf16 v[44:47], v[212:215], v[188:191], v[44:47]
	ds_read_b128 v[160:163], v202 offset:27648
	ds_read_b128 v[164:167], v202 offset:29952
	ds_read_b128 v[168:171], v202 offset:32256
	ds_read_b128 v[172:175], v202 offset:34560
	ds_read_b128 v[176:179], v202 offset:27712
	ds_read_b128 v[180:183], v202 offset:30016
	ds_read_b128 v[184:187], v202 offset:32320
	ds_read_b128 v[188:191], v202 offset:34624
	s_waitcnt lgkmcnt(7)
	v_mfma_f32_16x16x32_bf16 v[48:51], v[160:163], v[216:219], 0
	s_waitcnt lgkmcnt(6)
	v_mfma_f32_16x16x32_bf16 v[52:55], v[164:167], v[216:219], 0
	s_waitcnt lgkmcnt(5)
	v_mfma_f32_16x16x32_bf16 v[56:59], v[168:171], v[216:219], 0
	s_waitcnt lgkmcnt(4)
	v_mfma_f32_16x16x32_bf16 v[60:63], v[172:175], v[216:219], 0
	s_waitcnt lgkmcnt(3)
	v_mfma_f32_16x16x32_bf16 v[48:51], v[176:179], v[220:223], v[48:51]
	s_waitcnt lgkmcnt(2)
	v_mfma_f32_16x16x32_bf16 v[52:55], v[180:183], v[220:223], v[52:55]
	s_waitcnt lgkmcnt(1)
	v_mfma_f32_16x16x32_bf16 v[56:59], v[184:187], v[220:223], v[56:59]
	s_waitcnt lgkmcnt(0)
	v_mfma_f32_16x16x32_bf16 v[60:63], v[188:191], v[220:223], v[60:63]
	v_cvt_pk_bf16_f32 v244, -v32, -v33
	v_cvt_pk_bf16_f32 v245, -v34, -v35
	ds_write_b64 v204, v[244:245] offset:0
	v_cvt_pk_bf16_f32 v250, -v36, -v37
	v_cvt_pk_bf16_f32 v251, -v38, -v39
	ds_write_b64 v204, v[250:251] offset:4352
	v_cvt_pk_bf16_f32 v244, -v40, -v41
	v_cvt_pk_bf16_f32 v245, -v42, -v43
	ds_write_b64 v204, v[244:245] offset:8704
	v_cvt_pk_bf16_f32 v250, -v44, -v45
	v_cvt_pk_bf16_f32 v251, -v46, -v47
	ds_write_b64 v204, v[250:251] offset:13056
	s_waitcnt lgkmcnt(0)
	s_barrier
	s_waitcnt vmcnt(0)
	ds_write2_b64 v142, v[104:105], v[106:107] offset1:2
	ds_write2_b64 v143, v[108:109], v[110:111] offset1:2
	ds_write_b128 v146, v[112:115] offset:0
	ds_write_b128 v146, v[116:119] offset:9216
	ds_write2_b64 v144, v[120:121], v[122:123] offset1:2
	ds_write_b128 v146, v[124:127] offset:27648
	s_waitcnt lgkmcnt(0)
	s_mov_b32 s19, s18
	s_mov_b64 s[20:21], s[14:15]
	s_mov_b64 s[22:23], s[16:17]
	s_barrier
	s_mov_b32 s10, 0
.Lmy_scan_loop:
	s_add_u32 s12, s10, 2
	s_min_u32 s12, s12, 0x83
	s_sub_u32 s13, 3, s12
	s_sub_u32 s0, 0x87, s12
	s_cmp_lt_u32 s12, 4
	s_cselect_b32 s13, s13, s0
	s_cselect_b32 s18, 1, 0
	s_cmp_eq_u32 s2, 0
	s_cselect_b32 s12, s12, s13
	s_mul_i32 s13, s12, 0x60000
	s_cmp_eq_u32 s18, 1
	s_cselect_b32 s14, s4, s6
	s_cselect_b32 s15, s5, s7
	s_add_u32 s14, s14, s13
	s_addc_u32 s15, s15, 0
	s_mul_i32 s13, s12, 0x6400
	s_add_u32 s16, s8, s13
	s_addc_u32 s17, s9, 0
	s_mul_i32 s12, s18, 0x3800
	s_add_u32 s12, s12, 0x800
	s_mul_i32 s13, s18, 0x2e000
	s_sub_u32 s13, 0x30000, s13
	s_cmp_eq_u32 s18, 1
	s_cselect_b64 vcc, -1, 0
	s_add_u32 s36, s14, s12
	s_addc_u32 s37, s15, 0
	s_add_u32 s40, s36, s12
	s_addc_u32 s41, s37, 0
	s_add_u32 s38, s36, s13
	s_addc_u32 s39, s37, 0
	s_add_u32 s42, s40, s13
	s_addc_u32 s43, s41, 0
	s_add_u32 s46, s16, 0x2000
	s_addc_u32 s47, s17, 0
	v_cndmask_b32_e32 v151, v149, v148, vcc
	s_mul_i32 s13, s19, 0x2e000
	s_sub_u32 s13, 0x30000, s13
	s_cmp_eq_u32 s19, 1
	s_cselect_b64 vcc, -1, 0
	s_add_u32 s28, s20, s13
	s_addc_u32 s29, s21, 0
	s_add_u32 s30, s22, 0x4000
	s_addc_u32 s31, s23, 0
	s_add_u32 s34, s22, 0x6000
	s_addc_u32 s35, s23, 0
	v_cndmask_b32_e32 v150, v149, v148, vcc
	global_load_dwordx4 v[96:99], v150, s[20:21]
	global_load_dwordx4 v[100:103], v150, s[28:29]
	global_load_dwordx4 v[128:131], v148, s[30:31]
	s_cmp_lg_u32 s3, 0
	s_cbranch_scc1 .Lmy_sc_nog2
	global_load_dword v132, v147, s[34:35]
; __device__ __forceinline__ bf16x8 packfrag(f32x4 d0, f32x4 d1){ u32x4 t={pack2(d0[0],d0[1]),pack2(d0[2],d0[3]),pack2(d1[0],d1[1]),pack2(d1[2],d1[3])}; return __builtin_bit_cast(bf16x8,t); }
; #define MF(a,b,c) __builtin_amdgcn_mfma_f32_16x16x32_bf16(a,b,c,0,0,0)
; __device__ __forceinline__ void phase_scan(KP kp_){ asm volatile("" : "+s"(kp_)); const Params p=load_params(kp_);
;     ...
;       bf16x8 Sf[4];
;       _Pragma("unroll") for (int q=0;q<4;++q) Sf[q]=packfrag(Sacc[2*q],Sacc[2*q+1]);
;       f32x4 oacc[4];
;       _Pragma("unroll") for (int i=0;i<4;++i) oacc[i]=f32x4{0.f,0.f,0.f,0.f};
;       _Pragma("unroll") for (int q=0;q<4;++q){ int kb=(32*q+kg*4)*2;
;         _Pragma("unroll") for (int t=0;t<4;++t){
;           vn[t]=MF(lds64x2(SWB+(t*16+r)*272+kb), Sf[q], vn[t]);
;           oacc[t]=MF(lds64x2(SQ+(t*16+r)*272+kb), Sf[q], oacc[t]); } }
;       const float* gcs=(const float*)(smem+SGC);
;       float gl = d ? gcs[0] : gcs[63];
;       float gam=__expf(gl);
;       f32x4 vs[4];
;       _Pragma("unroll") for (int t=0;t<4;++t){ float4 g4=*(const float4*)(gcs+t*16+kg*4);
;         oacc[t][0]*=__expf(g4.x); oacc[t][1]*=__expf(g4.y); oacc[t][2]*=__expf(g4.z); oacc[t][3]*=__expf(g4.w);
;         vs[t][0]=vn[t][0]*__expf(gl-g4.x); vs[t][1]=vn[t][1]*__expf(gl-g4.y); vs[t][2]=vn[t][2]*__expf(gl-g4.z); vs[t][3]=vn[t][3]*__expf(gl-g4.w); }
;       bf16x8 Vf[2], Wf[2];
;       _Pragma("unroll") for (int q=0;q<2;++q){ Vf[q]=packfrag(vn[2*q],vn[2*q+1]); Wf[q]=packfrag(vs[2*q],vs[2*q+1]); }
;       _Pragma("unroll") for (int q=0;q<2;++q){ int kb=(32*q+kg*4)*2;
;         _Pragma("unroll") for (int t=0;t<4;++t) oacc[t]=MF(lds64x2(SAT+(t*16+r)*144+kb), Vf[q], oacc[t]); }
;       _Pragma("unroll") for (int m8=0;m8<8;++m8){ Sacc[m8][0]*=gam; Sacc[m8][1]*=gam; Sacc[m8][2]*=gam; Sacc[m8][3]*=gam; }
;       _Pragma("unroll") for (int q=0;q<2;++q){ int kb=(32*q+kg*4)*2;
;         _Pragma("unroll") for (int m8=0;m8<8;++m8) Sacc[m8]=MF(lds64x2(SKT+(m8*16+r)*144+kb), Wf[q], Sacc[m8]); }
.Lmy_sc_nog2:
	global_load_dwordx4 v[104:107], v151, s[36:37]
	global_load_dwordx4 v[108:111], v151, s[38:39]
	global_load_dwordx4 v[112:115], v151, s[40:41]
	global_load_dwordx4 v[116:119], v151, s[42:43]
	global_load_dwordx4 v[120:123], v148, s[16:17]
	global_load_dwordx4 v[124:127], v148, s[46:47]
	ds_read_b32 v152, v137 offset:64000
	ds_read_b128 v[160:163], v200 offset:0
	ds_read_b128 v[164:167], v200 offset:64
	ds_read_b128 v[168:171], v200 offset:128
	ds_read_b128 v[172:175], v200 offset:192
	ds_read_b128 v[176:179], v200 offset:4352
	ds_read_b128 v[180:183], v200 offset:4416
	ds_read_b128 v[184:187], v200 offset:4480
	ds_read_b128 v[188:191], v200 offset:4544
	ds_read_b128 v[224:227], v137 offset:63744
	ds_read_b128 v[228:231], v137 offset:63808
	v_cvt_pk_bf16_f32 v32, v0, v1
	v_cvt_pk_bf16_f32 v33, v2, v3
	v_cvt_pk_bf16_f32 v34, v4, v5
	v_cvt_pk_bf16_f32 v35, v6, v7
	v_cvt_pk_bf16_f32 v36, v8, v9
	v_cvt_pk_bf16_f32 v37, v10, v11
	v_cvt_pk_bf16_f32 v38, v12, v13
	v_cvt_pk_bf16_f32 v39, v14, v15
	v_cvt_pk_bf16_f32 v40, v16, v17
	v_cvt_pk_bf16_f32 v41, v18, v19
	v_cvt_pk_bf16_f32 v42, v20, v21
	v_cvt_pk_bf16_f32 v43, v22, v23
	v_cvt_pk_bf16_f32 v44, v24, v25
	v_cvt_pk_bf16_f32 v45, v26, v27
	v_cvt_pk_bf16_f32 v46, v28, v29
	v_cvt_pk_bf16_f32 v47, v30, v31
	s_waitcnt lgkmcnt(9)
	v_mfma_f32_16x16x32_bf16 v[48:51], v[160:163], v[32:35], v[48:51]
	ds_read_b128 v[192:195], v200 offset:8704
	v_mul_f32_e32 v0, v152, v0
	v_mul_f32_e32 v1, v152, v1
	s_waitcnt lgkmcnt(9)
	v_mfma_f32_16x16x32_bf16 v[48:51], v[164:167], v[36:39], v[48:51]
	ds_read_b128 v[196:199], v200 offset:8768
	v_mul_f32_e32 v2, v152, v2
	v_mul_f32_e32 v3, v152, v3
	s_waitcnt lgkmcnt(9)
	v_mfma_f32_16x16x32_bf16 v[48:51], v[168:171], v[40:43], v[48:51]
	ds_read_b128 v[160:163], v200 offset:8832
	v_mul_f32_e32 v4, v152, v4
	v_mul_f32_e32 v5, v152, v5
	ds_read_b128 v[232:235], v137 offset:63872
	s_waitcnt lgkmcnt(10)
	v_mfma_f32_16x16x32_bf16 v[48:51], v[172:175], v[44:47], v[48:51]
	ds_read_b128 v[164:167], v200 offset:8896
	v_mul_f32_e32 v6, v152, v6
	v_mul_f32_e32 v7, v152, v7
	s_waitcnt lgkmcnt(10)
	v_mfma_f32_16x16x32_bf16 v[52:55], v[176:179], v[32:35], v[52:55]
	ds_read_b128 v[168:171], v200 offset:13056
	v_mul_f32_e32 v8, v152, v8
	v_mul_f32_e32 v9, v152, v9
	ds_read_b128 v[236:239], v137 offset:63936
	s_waitcnt lgkmcnt(11)
	v_mfma_f32_16x16x32_bf16 v[52:55], v[180:183], v[36:39], v[52:55]
	ds_read_b128 v[172:175], v200 offset:13120
	v_mul_f32_e32 v10, v152, v10
	v_mul_f32_e32 v11, v152, v11
	s_waitcnt lgkmcnt(11)
	v_mfma_f32_16x16x32_bf16 v[52:55], v[184:187], v[40:43], v[52:55]
	ds_read_b128 v[176:179], v200 offset:13184
	v_mul_f32_e32 v12, v152, v12
	v_mul_f32_e32 v13, v152, v13
	s_waitcnt lgkmcnt(11)
	v_mfma_f32_16x16x32_bf16 v[52:55], v[188:191], v[44:47], v[52:55]
	ds_read_b128 v[180:183], v200 offset:13248
	v_mul_f32_e32 v14, v152, v14
	v_mul_f32_e32 v15, v152, v15
	s_waitcnt lgkmcnt(9)
	v_mfma_f32_16x16x32_bf16 v[56:59], v[192:195], v[32:35], v[56:59]
	ds_read_b128 v[184:187], v133 offset:0
	v_mul_f32_e32 v16, v152, v16
	v_mul_f32_e32 v17, v152, v17
	s_waitcnt lgkmcnt(9)
	v_mfma_f32_16x16x32_bf16 v[56:59], v[196:199], v[36:39], v[56:59]
	ds_read_b128 v[188:191], v133 offset:64
	v_mul_f32_e32 v18, v152, v18
	v_mul_f32_e32 v19, v152, v19
	s_waitcnt lgkmcnt(9)
	v_mfma_f32_16x16x32_bf16 v[56:59], v[160:163], v[40:43], v[56:59]
	ds_read_b128 v[192:195], v133 offset:128
	v_mul_f32_e32 v20, v152, v20
	v_mul_f32_e32 v21, v152, v21
	s_waitcnt lgkmcnt(8)
	v_mfma_f32_16x16x32_bf16 v[56:59], v[164:167], v[44:47], v[56:59]
	ds_read_b128 v[196:199], v133 offset:192
	v_mul_f32_e32 v22, v152, v22
	v_mul_f32_e32 v23, v152, v23
	s_waitcnt lgkmcnt(8)
	v_mfma_f32_16x16x32_bf16 v[60:63], v[168:171], v[32:35], v[60:63]
	ds_read_b128 v[160:163], v133 offset:4352
	v_mul_f32_e32 v24, v152, v24
	v_mul_f32_e32 v25, v152, v25
	s_waitcnt lgkmcnt(7)
	v_mfma_f32_16x16x32_bf16 v[60:63], v[172:175], v[36:39], v[60:63]
	ds_read_b128 v[164:167], v133 offset:4416
	v_mul_f32_e32 v26, v152, v26
	v_mul_f32_e32 v27, v152, v27
	s_waitcnt lgkmcnt(7)
	v_mfma_f32_16x16x32_bf16 v[60:63], v[176:179], v[40:43], v[60:63]
	ds_read_b128 v[168:171], v133 offset:4480
	v_mul_f32_e32 v28, v152, v28
	v_mul_f32_e32 v29, v152, v29
	s_waitcnt lgkmcnt(7)
	v_mfma_f32_16x16x32_bf16 v[60:63], v[180:183], v[44:47], v[60:63]
	ds_read_b128 v[172:175], v133 offset:4544
	v_mul_f32_e32 v30, v152, v30
	v_mul_f32_e32 v31, v152, v31
	s_waitcnt lgkmcnt(7)
	v_mfma_f32_16x16x32_bf16 v[64:67], v[184:187], v[32:35], 0
	ds_read_b128 v[176:179], v133 offset:8704
	v_mul_f32_e32 v224, v48, v224
	v_mul_f32_e32 v225, v49, v225
	s_waitcnt lgkmcnt(7)
	v_mfma_f32_16x16x32_bf16 v[64:67], v[188:191], v[36:39], v[64:67]
	ds_read_b128 v[180:183], v133 offset:8768
	v_mul_f32_e32 v226, v50, v226
	v_mul_f32_e32 v227, v51, v227
	s_waitcnt lgkmcnt(7)
	v_mfma_f32_16x16x32_bf16 v[64:67], v[192:195], v[40:43], v[64:67]
	ds_read_b128 v[184:187], v133 offset:8832
	v_cvt_pk_bf16_f32 v88, v48, v49
	v_cvt_pk_bf16_f32 v89, v50, v51
	s_waitcnt lgkmcnt(7)
	v_mfma_f32_16x16x32_bf16 v[64:67], v[196:199], v[44:47], v[64:67]
	ds_read_b128 v[188:191], v133 offset:8896
	v_cvt_pk_bf16_f32 v80, v224, v225
	v_cvt_pk_bf16_f32 v81, v226, v227
	s_waitcnt lgkmcnt(7)
	v_mfma_f32_16x16x32_bf16 v[68:71], v[160:163], v[32:35], 0
	ds_read_b128 v[192:195], v133 offset:13056
	v_mul_f32_e32 v228, v52, v228
	v_mul_f32_e32 v229, v53, v229
	s_waitcnt lgkmcnt(7)
	v_mfma_f32_16x16x32_bf16 v[68:71], v[164:167], v[36:39], v[68:71]
	ds_read_b128 v[196:199], v133 offset:13120
	v_mul_f32_e32 v230, v54, v230
	v_mul_f32_e32 v231, v55, v231
	s_waitcnt lgkmcnt(7)
; __device__ __forceinline__ unsigned pack2(float a, float b){ f32x2_t v={a,b}; bf16x2_t r=__builtin_convertvector(v,bf16x2_t); return __builtin_bit_cast(unsigned,r); }
; __device__ __forceinline__ bf16x8 packfrag(f32x4 d0, f32x4 d1){ u32x4 t={pack2(d0[0],d0[1]),pack2(d0[2],d0[3]),pack2(d1[0],d1[1]),pack2(d1[2],d1[3])}; return __builtin_bit_cast(bf16x8,t); }
; #define MF(a,b,c) __builtin_amdgcn_mfma_f32_16x16x32_bf16(a,b,c,0,0,0)
; __device__ __forceinline__ void phase_scan(KP kp_){ asm volatile("" : "+s"(kp_)); const Params p=load_params(kp_);
;     ...
;       _Pragma("unroll") for (int ks=0;ks<2;++ks){ int kb=(ks*32+kg*8)*2;
;         bf16x8 A=lds128(SKT+(wv*16+r)*144+kb);
;         bf16x8 Bv=lds128(SVT+(wv*16+r)*144+kb);
;         _Pragma("unroll") for (int t=0;t<4;++t){
;           wacc[t]=MF(A, lds128(STW+(t*16+r)*144+kb), wacc[t]);
;           vn[t]=MF(lds128(STU+(t*16+r)*144+kb), Bv, vn[t]); } }
;       _Pragma("unroll") for (int t=0;t<4;++t){ uint2 pk2; pk2.x=pack2(-wacc[t][0],-wacc[t][1]); pk2.y=pack2(-wacc[t][2],-wacc[t][3]);
;         *(uint2*)(smem+SWB+(t*16+r)*272+(wv*16+kg*4)*2)=pk2; }
;     ...
;       _Pragma("unroll") for (int t=0;t<4;++t){ float4 g4=*(const float4*)(gcs+t*16+kg*4);
;         oacc[t][0]*=__expf(g4.x); oacc[t][1]*=__expf(g4.y); oacc[t][2]*=__expf(g4.z); oacc[t][3]*=__expf(g4.w);
;         vs[t][0]=vn[t][0]*__expf(gl-g4.x); vs[t][1]=vn[t][1]*__expf(gl-g4.y); vs[t][2]=vn[t][2]*__expf(gl-g4.z); vs[t][3]=vn[t][3]*__expf(gl-g4.w); }
;       bf16x8 Vf[2], Wf[2];
;       _Pragma("unroll") for (int q=0;q<2;++q){ Vf[q]=packfrag(vn[2*q],vn[2*q+1]); Wf[q]=packfrag(vs[2*q],vs[2*q+1]); }
;       _Pragma("unroll") for (int q=0;q<2;++q){ int kb=(32*q+kg*4)*2;
;         _Pragma("unroll") for (int t=0;t<4;++t) oacc[t]=MF(lds64x2(SAT+(t*16+r)*144+kb), Vf[q], oacc[t]); }
;       _Pragma("unroll") for (int m8=0;m8<8;++m8){ Sacc[m8][0]*=gam; Sacc[m8][1]*=gam; Sacc[m8][2]*=gam; Sacc[m8][3]*=gam; }
;       _Pragma("unroll") for (int q=0;q<2;++q){ int kb=(32*q+kg*4)*2;
;         _Pragma("unroll") for (int m8=0;m8<8;++m8) Sacc[m8]=MF(lds64x2(SKT+(m8*16+r)*144+kb), Wf[q], Sacc[m8]); }
	v_mfma_f32_16x16x32_bf16 v[68:71], v[168:171], v[40:43], v[68:71]
	ds_read_b128 v[160:163], v133 offset:13184
	v_cvt_pk_bf16_f32 v90, v52, v53
	v_cvt_pk_bf16_f32 v91, v54, v55
	s_waitcnt lgkmcnt(7)
	v_mfma_f32_16x16x32_bf16 v[68:71], v[172:175], v[44:47], v[68:71]
	ds_read_b128 v[164:167], v133 offset:13248
	v_cvt_pk_bf16_f32 v82, v228, v229
	v_cvt_pk_bf16_f32 v83, v230, v231
	s_waitcnt lgkmcnt(7)
	v_mfma_f32_16x16x32_bf16 v[72:75], v[176:179], v[32:35], 0
	ds_read_b128 v[168:171], v134 offset:17408
	v_mul_f32_e32 v232, v56, v232
	v_mul_f32_e32 v233, v57, v233
	s_waitcnt lgkmcnt(7)
	v_mfma_f32_16x16x32_bf16 v[72:75], v[180:183], v[36:39], v[72:75]
	ds_read_b128 v[172:175], v134 offset:19712
	v_mul_f32_e32 v234, v58, v234
	v_mul_f32_e32 v235, v59, v235
	s_waitcnt lgkmcnt(7)
	v_mfma_f32_16x16x32_bf16 v[72:75], v[184:187], v[40:43], v[72:75]
	ds_read_b128 v[176:179], v134 offset:22016
	v_cvt_pk_bf16_f32 v92, v56, v57
	v_cvt_pk_bf16_f32 v93, v58, v59
	s_waitcnt lgkmcnt(7)
	v_mfma_f32_16x16x32_bf16 v[72:75], v[188:191], v[44:47], v[72:75]
	ds_read_b128 v[180:183], v134 offset:24320
	v_cvt_pk_bf16_f32 v84, v232, v233
	v_cvt_pk_bf16_f32 v85, v234, v235
	s_waitcnt lgkmcnt(7)
	v_mfma_f32_16x16x32_bf16 v[76:79], v[192:195], v[32:35], 0
	ds_read_b128 v[184:187], v134 offset:26624
	v_mul_f32_e32 v236, v60, v236
	v_mul_f32_e32 v237, v61, v237
	s_waitcnt lgkmcnt(7)
	v_mfma_f32_16x16x32_bf16 v[76:79], v[196:199], v[36:39], v[76:79]
	ds_read_b128 v[188:191], v134 offset:28928
	v_mul_f32_e32 v238, v62, v238
	v_mul_f32_e32 v239, v63, v239
	s_waitcnt lgkmcnt(7)
	v_mfma_f32_16x16x32_bf16 v[76:79], v[160:163], v[40:43], v[76:79]
	ds_read_b128 v[192:195], v134 offset:31232
	v_cvt_pk_bf16_f32 v94, v60, v61
	v_cvt_pk_bf16_f32 v95, v62, v63
	s_waitcnt lgkmcnt(7)
	v_mfma_f32_16x16x32_bf16 v[76:79], v[164:167], v[44:47], v[76:79]
	ds_read_b128 v[196:199], v134 offset:33536
	v_cvt_pk_bf16_f32 v86, v236, v237
	v_cvt_pk_bf16_f32 v87, v238, v239
	s_waitcnt lgkmcnt(7)
	v_mfma_f32_16x16x32_bf16 v[0:3], v[168:171], v[80:83], v[0:3]
	ds_read_b128 v[160:163], v134 offset:17472
	ds_read_b128 v[224:227], v137 offset:63488
	s_waitcnt lgkmcnt(8)
	v_mfma_f32_16x16x32_bf16 v[4:7], v[172:175], v[80:83], v[4:7]
	ds_read_b128 v[164:167], v134 offset:19776
	ds_read_b128 v[228:231], v137 offset:63552
	s_waitcnt lgkmcnt(9)
	v_mfma_f32_16x16x32_bf16 v[8:11], v[176:179], v[80:83], v[8:11]
	ds_read_b128 v[168:171], v134 offset:22080
	ds_read_b128 v[232:235], v137 offset:63616
	s_waitcnt lgkmcnt(10)
	v_mfma_f32_16x16x32_bf16 v[12:15], v[180:183], v[80:83], v[12:15]
	ds_read_b128 v[172:175], v134 offset:24384
	ds_read_b128 v[236:239], v137 offset:63680
	s_waitcnt lgkmcnt(11)
	v_mfma_f32_16x16x32_bf16 v[16:19], v[184:187], v[80:83], v[16:19]
	ds_read_b128 v[176:179], v134 offset:26688
	s_waitcnt lgkmcnt(11)
	v_mfma_f32_16x16x32_bf16 v[20:23], v[188:191], v[80:83], v[20:23]
	ds_read_b128 v[180:183], v134 offset:28992
	s_waitcnt lgkmcnt(11)
	v_mfma_f32_16x16x32_bf16 v[24:27], v[192:195], v[80:83], v[24:27]
	ds_read_b128 v[184:187], v134 offset:31296
	s_waitcnt lgkmcnt(11)
	v_mfma_f32_16x16x32_bf16 v[28:31], v[196:199], v[80:83], v[28:31]
	ds_read_b128 v[188:191], v134 offset:33600
	s_waitcnt lgkmcnt(11)
	v_mfma_f32_16x16x32_bf16 v[0:3], v[160:163], v[84:87], v[0:3]
	ds_read_b128 v[192:195], v134 offset:54272
	s_waitcnt lgkmcnt(11)
	v_mul_f32_e32 v64, v64, v224
	v_mul_f32_e32 v65, v65, v225
	s_waitcnt lgkmcnt(10)
	v_mfma_f32_16x16x32_bf16 v[4:7], v[164:167], v[84:87], v[4:7]
	ds_read_b128 v[196:199], v134 offset:56576
	v_mul_f32_e32 v66, v66, v226
	v_mul_f32_e32 v67, v67, v227
	s_waitcnt lgkmcnt(9)
	v_mfma_f32_16x16x32_bf16 v[8:11], v[168:171], v[84:87], v[8:11]
	ds_read_b128 v[160:163], v134 offset:58880
	v_mul_f32_e32 v68, v68, v228
	v_mul_f32_e32 v69, v69, v229
	s_waitcnt lgkmcnt(8)
	v_mfma_f32_16x16x32_bf16 v[12:15], v[172:175], v[84:87], v[12:15]
	ds_read_b128 v[164:167], v134 offset:61184
	v_mul_f32_e32 v70, v70, v230
	v_mul_f32_e32 v71, v71, v231
	s_waitcnt lgkmcnt(7)
	v_mfma_f32_16x16x32_bf16 v[16:19], v[176:179], v[84:87], v[16:19]
	ds_read_b128 v[168:171], v134 offset:54336
	v_mul_f32_e32 v72, v72, v232
	v_mul_f32_e32 v73, v73, v233
	ds_read_b128 v[208:211], v135 offset:35840
	s_waitcnt lgkmcnt(8)
	v_mfma_f32_16x16x32_bf16 v[20:23], v[180:183], v[84:87], v[20:23]
	ds_read_b128 v[172:175], v134 offset:56640
	v_mul_f32_e32 v74, v74, v234
	v_mul_f32_e32 v75, v75, v235
	ds_read_b128 v[212:215], v135 offset:35904
	s_waitcnt lgkmcnt(9)
	v_mfma_f32_16x16x32_bf16 v[24:27], v[184:187], v[84:87], v[24:27]
	ds_read_b128 v[176:179], v134 offset:58944
	v_mul_f32_e32 v76, v76, v236
	v_mul_f32_e32 v77, v77, v237
	ds_read_b128 v[216:219], v203 offset:0
	s_waitcnt lgkmcnt(10)
	v_mfma_f32_16x16x32_bf16 v[28:31], v[188:191], v[84:87], v[28:31]
	ds_read_b128 v[180:183], v134 offset:61248
	v_mul_f32_e32 v78, v78, v238
	v_mul_f32_e32 v79, v79, v239
	ds_read_b128 v[220:223], v203 offset:64
	s_waitcnt lgkmcnt(11)
	v_mfma_f32_16x16x32_bf16 v[64:67], v[192:195], v[88:91], v[64:67]
	ds_read_b128 v[184:187], v202 offset:18432
	s_waitcnt lgkmcnt(11)
	v_mfma_f32_16x16x32_bf16 v[68:71], v[196:199], v[88:91], v[68:71]
	ds_read_b128 v[188:191], v202 offset:20736
	s_waitcnt lgkmcnt(11)
	v_mfma_f32_16x16x32_bf16 v[72:75], v[160:163], v[88:91], v[72:75]
	ds_read_b128 v[192:195], v202 offset:23040
	s_waitcnt lgkmcnt(11)
	v_mfma_f32_16x16x32_bf16 v[76:79], v[164:167], v[88:91], v[76:79]
	ds_read_b128 v[196:199], v202 offset:25344
	s_waitcnt lgkmcnt(11)
	v_mfma_f32_16x16x32_bf16 v[64:67], v[168:171], v[92:95], v[64:67]
	ds_read_b128 v[160:163], v202 offset:18496
	s_waitcnt lgkmcnt(10)
; __device__ __forceinline__ unsigned pack2(float a, float b){ f32x2_t v={a,b}; bf16x2_t r=__builtin_convertvector(v,bf16x2_t); return __builtin_bit_cast(unsigned,r); }
; #define MF(a,b,c) __builtin_amdgcn_mfma_f32_16x16x32_bf16(a,b,c,0,0,0)
; __device__ __forceinline__ void phase_scan(KP kp_){ asm volatile("" : "+s"(kp_)); const Params p=load_params(kp_);
;     ...
;       _Pragma("unroll") for (int ks=0;ks<2;++ks){ int kb=(ks*32+kg*8)*2;
;         bf16x8 A=lds128(SKT+(wv*16+r)*144+kb);
;         bf16x8 Bv=lds128(SVT+(wv*16+r)*144+kb);
;         _Pragma("unroll") for (int t=0;t<4;++t){
;           wacc[t]=MF(A, lds128(STW+(t*16+r)*144+kb), wacc[t]);
;           vn[t]=MF(lds128(STU+(t*16+r)*144+kb), Bv, vn[t]); } }
;       _Pragma("unroll") for (int t=0;t<4;++t){ uint2 pk2; pk2.x=pack2(-wacc[t][0],-wacc[t][1]); pk2.y=pack2(-wacc[t][2],-wacc[t][3]);
;         *(uint2*)(smem+SWB+(t*16+r)*272+(wv*16+kg*4)*2)=pk2; }
;     ...
;       if (s>=4){ int cidx=4+(d?131-s:s-4); char* op=tabase+(size_t)((b*8+h)*132+cidx)*TA_STRIDE;
;         _Pragma("unroll") for (int t=0;t<4;++t) _Pragma("unroll") for (int j=0;j<4;++j)
;           *(u16*)(op+((t*16+kg*4+j)*128+wv*16+r)*2)=f2bf(oacc[t][j]); }
;         __syncthreads();
;         FILL(A);
;         __syncthreads();
;       }
;       { const int s=s2+1;
;         if (s+1<132) PREFETCH(A,s+1);
	v_mfma_f32_16x16x32_bf16 v[68:71], v[172:175], v[92:95], v[68:71]
	ds_read_b128 v[164:167], v202 offset:20800
	s_waitcnt lgkmcnt(9)
	v_mfma_f32_16x16x32_bf16 v[72:75], v[176:179], v[92:95], v[72:75]
	ds_read_b128 v[168:171], v202 offset:23104
	s_waitcnt lgkmcnt(8)
	v_mfma_f32_16x16x32_bf16 v[76:79], v[180:183], v[92:95], v[76:79]
	ds_read_b128 v[172:175], v202 offset:25408
	s_waitcnt lgkmcnt(7)
	v_mfma_f32_16x16x32_bf16 v[32:35], v[208:211], v[184:187], 0
	ds_read_b128 v[176:179], v202 offset:27648
	s_waitcnt lgkmcnt(7)
	v_mfma_f32_16x16x32_bf16 v[36:39], v[208:211], v[188:191], 0
	ds_read_b128 v[180:183], v202 offset:29952
	s_waitcnt lgkmcnt(7)
	v_mfma_f32_16x16x32_bf16 v[40:43], v[208:211], v[192:195], 0
	ds_read_b128 v[184:187], v202 offset:32256
	s_waitcnt lgkmcnt(7)
	v_mfma_f32_16x16x32_bf16 v[44:47], v[208:211], v[196:199], 0
	ds_read_b128 v[188:191], v202 offset:34560
	s_waitcnt lgkmcnt(7)
	v_mfma_f32_16x16x32_bf16 v[32:35], v[212:215], v[160:163], v[32:35]
	ds_read_b128 v[192:195], v202 offset:27712
	s_waitcnt lgkmcnt(7)
	v_mfma_f32_16x16x32_bf16 v[36:39], v[212:215], v[164:167], v[36:39]
	ds_read_b128 v[196:199], v202 offset:30016
	s_waitcnt lgkmcnt(7)
	v_mfma_f32_16x16x32_bf16 v[40:43], v[212:215], v[168:171], v[40:43]
	ds_read_b128 v[160:163], v202 offset:32320
	s_waitcnt lgkmcnt(7)
	v_mfma_f32_16x16x32_bf16 v[44:47], v[212:215], v[172:175], v[44:47]
	ds_read_b128 v[164:167], v202 offset:34624
	s_waitcnt lgkmcnt(7)
	v_mfma_f32_16x16x32_bf16 v[48:51], v[176:179], v[216:219], 0
	s_waitcnt lgkmcnt(6)
	v_mfma_f32_16x16x32_bf16 v[52:55], v[180:183], v[216:219], 0
	s_waitcnt vmcnt(0)
	s_add_u32 s12, s10, 0
	s_cmp_lt_u32 s12, 4
	s_cbranch_scc1 .Lmy_sc_nost3
	v_cvt_pk_bf16_f32 v246, v64, v65
	v_cvt_pk_bf16_f32 v247, v66, v67
	global_store_short v156, v246, s[24:25]
	global_store_short_d16_hi v156, v246, s[24:25] offset:256
	global_store_short v156, v247, s[24:25] offset:512
	global_store_short_d16_hi v156, v247, s[24:25] offset:768
	v_cvt_pk_bf16_f32 v248, v68, v69
	v_cvt_pk_bf16_f32 v249, v70, v71
	global_store_short v157, v248, s[24:25]
	global_store_short_d16_hi v157, v248, s[24:25] offset:256
	global_store_short v157, v249, s[24:25] offset:512
	global_store_short_d16_hi v157, v249, s[24:25] offset:768
	s_nop 0
	v_cvt_pk_bf16_f32 v246, v72, v73
	v_cvt_pk_bf16_f32 v247, v74, v75
	global_store_short v158, v246, s[24:25]
	global_store_short_d16_hi v158, v246, s[24:25] offset:256
	global_store_short v158, v247, s[24:25] offset:512
	global_store_short_d16_hi v158, v247, s[24:25] offset:768
	v_cvt_pk_bf16_f32 v248, v76, v77
	v_cvt_pk_bf16_f32 v249, v78, v79
	global_store_short v159, v248, s[24:25]
	global_store_short_d16_hi v159, v248, s[24:25] offset:256
	global_store_short v159, v249, s[24:25] offset:512
	global_store_short_d16_hi v159, v249, s[24:25] offset:768
.Lmy_sc_nost3:
	s_waitcnt lgkmcnt(5)
	v_mfma_f32_16x16x32_bf16 v[56:59], v[184:187], v[216:219], 0
	s_waitcnt lgkmcnt(4)
	v_mfma_f32_16x16x32_bf16 v[60:63], v[188:191], v[216:219], 0
	s_waitcnt lgkmcnt(3)
	v_mfma_f32_16x16x32_bf16 v[48:51], v[192:195], v[220:223], v[48:51]
	v_cvt_pk_bf16_f32 v244, -v32, -v33
	v_cvt_pk_bf16_f32 v245, -v34, -v35
	ds_write_b64 v205, v[244:245] offset:0
	s_waitcnt lgkmcnt(3)
	v_mfma_f32_16x16x32_bf16 v[52:55], v[196:199], v[220:223], v[52:55]
	v_cvt_pk_bf16_f32 v250, -v36, -v37
	v_cvt_pk_bf16_f32 v251, -v38, -v39
	ds_write_b64 v205, v[250:251] offset:4352
	s_waitcnt lgkmcnt(3)
	v_mfma_f32_16x16x32_bf16 v[56:59], v[160:163], v[220:223], v[56:59]
	v_cvt_pk_bf16_f32 v244, -v40, -v41
	v_cvt_pk_bf16_f32 v245, -v42, -v43
	ds_write_b64 v205, v[244:245] offset:8704
	s_waitcnt lgkmcnt(3)
	v_mfma_f32_16x16x32_bf16 v[60:63], v[164:167], v[220:223], v[60:63]
	v_cvt_pk_bf16_f32 v250, -v44, -v45
	v_cvt_pk_bf16_f32 v251, -v46, -v47
	ds_write_b64 v205, v[250:251] offset:13056
	s_waitcnt lgkmcnt(0)
	s_barrier
	ds_write2_b64 v138, v[96:97], v[98:99] offset1:2
	ds_write2_b64 v139, v[100:101], v[102:103] offset1:2
	ds_write2_b64 v145, v[128:129], v[130:131] offset1:2
	s_cmp_lg_u32 s3, 0
	s_cbranch_scc1 .Lmy_sc_noe4
	v_mul_f32_e32 v240, 0x3fb8aa3b, v132
	v_readlane_b32 s12, v132, s11
	s_nop 0
	v_exp_f32_e32 v240, v240
	s_nop 1
	v_sub_f32_e32 v241, s12, v132
	v_mov_b32_e32 v242, s12
	s_nop 0
	v_mul_f32_e32 v241, 0x3fb8aa3b, v241
	v_mul_f32_e32 v242, 0x3fb8aa3b, v242
	s_nop 0
	v_exp_f32_e32 v241, v241
	v_exp_f32_e32 v242, v242
	s_nop 1
	ds_write_b32 v147, v240 offset:63488
	ds_write_b32 v147, v241 offset:63744
	ds_write_b32 v147, v242 offset:64000
.Lmy_sc_noe4:
	ds_write2_b64 v140, v[104:105], v[106:107] offset1:2
	ds_write2_b64 v141, v[108:109], v[110:111] offset1:2
	ds_write_b128 v146, v[112:115] offset:0
	ds_write_b128 v146, v[116:119] offset:9216
	ds_write2_b64 v144, v[120:121], v[122:123] offset1:2
	ds_write_b128 v146, v[124:127] offset:27648
	s_waitcnt lgkmcnt(0)
	s_mov_b64 s[24:25], s[22:23]
	s_mov_b32 s19, s18
	s_mov_b64 s[20:21], s[14:15]
	s_mov_b64 s[22:23], s[16:17]
	s_barrier
	s_add_u32 s12, s10, 3
	s_min_u32 s12, s12, 0x83
	s_sub_u32 s13, 3, s12
	s_sub_u32 s0, 0x87, s12
	s_cmp_lt_u32 s12, 4
	s_cselect_b32 s13, s13, s0
	s_cselect_b32 s18, 1, 0
	s_cmp_eq_u32 s2, 0
	s_cselect_b32 s12, s12, s13
	s_mul_i32 s13, s12, 0x60000
	s_cmp_eq_u32 s18, 1
	s_cselect_b32 s14, s4, s6
	s_cselect_b32 s15, s5, s7
	s_add_u32 s14, s14, s13
	s_addc_u32 s15, s15, 0
	s_mul_i32 s13, s12, 0x6400
	s_add_u32 s16, s8, s13
	s_addc_u32 s17, s9, 0
	s_mul_i32 s12, s18, 0x3800
	s_add_u32 s12, s12, 0x800
	s_mul_i32 s13, s18, 0x2e000
	s_sub_u32 s13, 0x30000, s13
	s_cmp_eq_u32 s18, 1
	s_cselect_b64 vcc, -1, 0
	s_add_u32 s36, s14, s12
	s_addc_u32 s37, s15, 0
	s_add_u32 s40, s36, s12
	s_addc_u32 s41, s37, 0
	s_add_u32 s38, s36, s13
	s_addc_u32 s39, s37, 0
	s_add_u32 s42, s40, s13
	s_addc_u32 s43, s41, 0
	s_add_u32 s46, s16, 0x2000
	s_addc_u32 s47, s17, 0
	v_cndmask_b32_e32 v151, v149, v148, vcc
	s_mul_i32 s13, s19, 0x2e000
	s_sub_u32 s13, 0x30000, s13
	s_cmp_eq_u32 s19, 1
	s_cselect_b64 vcc, -1, 0
	s_add_u32 s28, s20, s13
	s_addc_u32 s29, s21, 0
	s_add_u32 s30, s22, 0x4000
	s_addc_u32 s31, s23, 0
	s_add_u32 s34, s22, 0x6000
	s_addc_u32 s35, s23, 0
	v_cndmask_b32_e32 v150, v149, v148, vcc
	global_load_dwordx4 v[96:99], v150, s[20:21]
	global_load_dwordx4 v[100:103], v150, s[28:29]
	global_load_dwordx4 v[128:131], v148, s[30:31]
	s_cmp_lg_u32 s3, 0
	s_cbranch_scc1 .Lmy_sc_nog5
	global_load_dword v132, v147, s[34:35]
; __device__ __forceinline__ unsigned pack2(float a, float b){ f32x2_t v={a,b}; bf16x2_t r=__builtin_convertvector(v,bf16x2_t); return __builtin_bit_cast(unsigned,r); }
; __device__ __forceinline__ bf16x8 packfrag(f32x4 d0, f32x4 d1){ u32x4 t={pack2(d0[0],d0[1]),pack2(d0[2],d0[3]),pack2(d1[0],d1[1]),pack2(d1[2],d1[3])}; return __builtin_bit_cast(bf16x8,t); }
; #define MF(a,b,c) __builtin_amdgcn_mfma_f32_16x16x32_bf16(a,b,c,0,0,0)
; __device__ __forceinline__ void phase_scan(KP kp_){ asm volatile("" : "+s"(kp_)); const Params p=load_params(kp_);
;     ...
;       { const int s=s2+1;
;         if (s+1<132) PREFETCH(A,s+1);
;       f32x4 wacc[4], vn[4];
;       _Pragma("unroll") for (int i=0;i<4;++i){ wacc[i]=f32x4{0.f,0.f,0.f,0.f}; vn[i]=f32x4{0.f,0.f,0.f,0.f}; }
;       _Pragma("unroll") for (int ks=0;ks<2;++ks){ int kb=(ks*32+kg*8)*2;
;         bf16x8 A=lds128(SKT+(wv*16+r)*144+kb);
;         bf16x8 Bv=lds128(SVT+(wv*16+r)*144+kb);
;         _Pragma("unroll") for (int t=0;t<4;++t){
;           wacc[t]=MF(A, lds128(STW+(t*16+r)*144+kb), wacc[t]);
;           vn[t]=MF(lds128(STU+(t*16+r)*144+kb), Bv, vn[t]); } }
;       _Pragma("unroll") for (int t=0;t<4;++t){ uint2 pk2; pk2.x=pack2(-wacc[t][0],-wacc[t][1]); pk2.y=pack2(-wacc[t][2],-wacc[t][3]);
;         *(uint2*)(smem+SWB+(t*16+r)*272+(wv*16+kg*4)*2)=pk2; }
;       __syncthreads();
;       bf16x8 Sf[4];
;       _Pragma("unroll") for (int q=0;q<4;++q) Sf[q]=packfrag(Sacc[2*q],Sacc[2*q+1]);
;       f32x4 oacc[4];
;       _Pragma("unroll") for (int i=0;i<4;++i) oacc[i]=f32x4{0.f,0.f,0.f,0.f};
;       _Pragma("unroll") for (int q=0;q<4;++q){ int kb=(32*q+kg*4)*2;
;         _Pragma("unroll") for (int t=0;t<4;++t){
;           vn[t]=MF(lds64x2(SWB+(t*16+r)*272+kb), Sf[q], vn[t]);
;           oacc[t]=MF(lds64x2(SQ+(t*16+r)*272+kb), Sf[q], oacc[t]); } }
.Lmy_sc_nog5:
	global_load_dwordx4 v[104:107], v151, s[36:37]
	global_load_dwordx4 v[108:111], v151, s[38:39]
	global_load_dwordx4 v[112:115], v151, s[40:41]
	global_load_dwordx4 v[116:119], v151, s[42:43]
	global_load_dwordx4 v[120:123], v148, s[16:17]
	global_load_dwordx4 v[124:127], v148, s[46:47]
	ds_read_b32 v152, v137 offset:64000
	ds_read_b128 v[160:163], v201 offset:0
	ds_read_b128 v[164:167], v201 offset:64
	ds_read_b128 v[168:171], v201 offset:128
	ds_read_b128 v[172:175], v201 offset:192
	ds_read_b128 v[176:179], v201 offset:4352
	ds_read_b128 v[180:183], v201 offset:4416
	ds_read_b128 v[184:187], v201 offset:4480
	ds_read_b128 v[188:191], v201 offset:4544
	ds_read_b128 v[224:227], v137 offset:63744
	ds_read_b128 v[228:231], v137 offset:63808
	v_cvt_pk_bf16_f32 v32, v0, v1
	v_cvt_pk_bf16_f32 v33, v2, v3
	v_cvt_pk_bf16_f32 v34, v4, v5
	v_cvt_pk_bf16_f32 v35, v6, v7
	v_cvt_pk_bf16_f32 v36, v8, v9
	v_cvt_pk_bf16_f32 v37, v10, v11
	v_cvt_pk_bf16_f32 v38, v12, v13
	v_cvt_pk_bf16_f32 v39, v14, v15
	v_cvt_pk_bf16_f32 v40, v16, v17
	v_cvt_pk_bf16_f32 v41, v18, v19
	v_cvt_pk_bf16_f32 v42, v20, v21
	v_cvt_pk_bf16_f32 v43, v22, v23
	v_cvt_pk_bf16_f32 v44, v24, v25
	v_cvt_pk_bf16_f32 v45, v26, v27
	v_cvt_pk_bf16_f32 v46, v28, v29
	v_cvt_pk_bf16_f32 v47, v30, v31
	s_waitcnt lgkmcnt(9)
	v_mfma_f32_16x16x32_bf16 v[48:51], v[160:163], v[32:35], v[48:51]
	ds_read_b128 v[192:195], v201 offset:8704
	v_mul_f32_e32 v0, v152, v0
	v_mul_f32_e32 v1, v152, v1
	s_waitcnt lgkmcnt(9)
	v_mfma_f32_16x16x32_bf16 v[48:51], v[164:167], v[36:39], v[48:51]
	ds_read_b128 v[196:199], v201 offset:8768
	v_mul_f32_e32 v2, v152, v2
	v_mul_f32_e32 v3, v152, v3
	s_waitcnt lgkmcnt(9)
	v_mfma_f32_16x16x32_bf16 v[48:51], v[168:171], v[40:43], v[48:51]
	ds_read_b128 v[160:163], v201 offset:8832
	v_mul_f32_e32 v4, v152, v4
	v_mul_f32_e32 v5, v152, v5
	ds_read_b128 v[232:235], v137 offset:63872
	s_waitcnt lgkmcnt(10)
	v_mfma_f32_16x16x32_bf16 v[48:51], v[172:175], v[44:47], v[48:51]
	ds_read_b128 v[164:167], v201 offset:8896
	v_mul_f32_e32 v6, v152, v6
	v_mul_f32_e32 v7, v152, v7
	s_waitcnt lgkmcnt(10)
	v_mfma_f32_16x16x32_bf16 v[52:55], v[176:179], v[32:35], v[52:55]
	ds_read_b128 v[168:171], v201 offset:13056
	v_mul_f32_e32 v8, v152, v8
	v_mul_f32_e32 v9, v152, v9
	ds_read_b128 v[236:239], v137 offset:63936
	s_waitcnt lgkmcnt(11)
	v_mfma_f32_16x16x32_bf16 v[52:55], v[180:183], v[36:39], v[52:55]
	ds_read_b128 v[172:175], v201 offset:13120
	v_mul_f32_e32 v10, v152, v10
	v_mul_f32_e32 v11, v152, v11
	s_waitcnt lgkmcnt(11)
	v_mfma_f32_16x16x32_bf16 v[52:55], v[184:187], v[40:43], v[52:55]
	ds_read_b128 v[176:179], v201 offset:13184
	v_mul_f32_e32 v12, v152, v12
	v_mul_f32_e32 v13, v152, v13
	s_waitcnt lgkmcnt(11)
	v_mfma_f32_16x16x32_bf16 v[52:55], v[188:191], v[44:47], v[52:55]
	ds_read_b128 v[180:183], v201 offset:13248
	v_mul_f32_e32 v14, v152, v14
	v_mul_f32_e32 v15, v152, v15
	s_waitcnt lgkmcnt(9)
	v_mfma_f32_16x16x32_bf16 v[56:59], v[192:195], v[32:35], v[56:59]
	ds_read_b128 v[184:187], v133 offset:0
	v_mul_f32_e32 v16, v152, v16
	v_mul_f32_e32 v17, v152, v17
	s_waitcnt lgkmcnt(9)
	v_mfma_f32_16x16x32_bf16 v[56:59], v[196:199], v[36:39], v[56:59]
	ds_read_b128 v[188:191], v133 offset:64
	v_mul_f32_e32 v18, v152, v18
	v_mul_f32_e32 v19, v152, v19
	s_waitcnt lgkmcnt(9)
	v_mfma_f32_16x16x32_bf16 v[56:59], v[160:163], v[40:43], v[56:59]
	ds_read_b128 v[192:195], v133 offset:128
	v_mul_f32_e32 v20, v152, v20
	v_mul_f32_e32 v21, v152, v21
	s_waitcnt lgkmcnt(8)
	v_mfma_f32_16x16x32_bf16 v[56:59], v[164:167], v[44:47], v[56:59]
	ds_read_b128 v[196:199], v133 offset:192
	v_mul_f32_e32 v22, v152, v22
	v_mul_f32_e32 v23, v152, v23
	s_waitcnt lgkmcnt(8)
	v_mfma_f32_16x16x32_bf16 v[60:63], v[168:171], v[32:35], v[60:63]
	ds_read_b128 v[160:163], v133 offset:4352
	v_mul_f32_e32 v24, v152, v24
	v_mul_f32_e32 v25, v152, v25
	s_waitcnt lgkmcnt(7)
	v_mfma_f32_16x16x32_bf16 v[60:63], v[172:175], v[36:39], v[60:63]
	ds_read_b128 v[164:167], v133 offset:4416
	v_mul_f32_e32 v26, v152, v26
	v_mul_f32_e32 v27, v152, v27
	s_waitcnt lgkmcnt(7)
	v_mfma_f32_16x16x32_bf16 v[60:63], v[176:179], v[40:43], v[60:63]
	ds_read_b128 v[168:171], v133 offset:4480
	v_mul_f32_e32 v28, v152, v28
	v_mul_f32_e32 v29, v152, v29
	s_waitcnt lgkmcnt(7)
	v_mfma_f32_16x16x32_bf16 v[60:63], v[180:183], v[44:47], v[60:63]
	ds_read_b128 v[172:175], v133 offset:4544
	v_mul_f32_e32 v30, v152, v30
	v_mul_f32_e32 v31, v152, v31
	s_waitcnt lgkmcnt(7)
	v_mfma_f32_16x16x32_bf16 v[64:67], v[184:187], v[32:35], 0
	ds_read_b128 v[176:179], v133 offset:8704
	v_mul_f32_e32 v224, v48, v224
	v_mul_f32_e32 v225, v49, v225
	s_waitcnt lgkmcnt(7)
	v_mfma_f32_16x16x32_bf16 v[64:67], v[188:191], v[36:39], v[64:67]
	ds_read_b128 v[180:183], v133 offset:8768
	v_mul_f32_e32 v226, v50, v226
	v_mul_f32_e32 v227, v51, v227
	s_waitcnt lgkmcnt(7)
	v_mfma_f32_16x16x32_bf16 v[64:67], v[192:195], v[40:43], v[64:67]
	ds_read_b128 v[184:187], v133 offset:8832
	v_cvt_pk_bf16_f32 v88, v48, v49
	v_cvt_pk_bf16_f32 v89, v50, v51
	s_waitcnt lgkmcnt(7)
	v_mfma_f32_16x16x32_bf16 v[64:67], v[196:199], v[44:47], v[64:67]
	ds_read_b128 v[188:191], v133 offset:8896
	v_cvt_pk_bf16_f32 v80, v224, v225
	v_cvt_pk_bf16_f32 v81, v226, v227
	s_waitcnt lgkmcnt(7)
	v_mfma_f32_16x16x32_bf16 v[68:71], v[160:163], v[32:35], 0
	ds_read_b128 v[192:195], v133 offset:13056
	v_mul_f32_e32 v228, v52, v228
	v_mul_f32_e32 v229, v53, v229
	s_waitcnt lgkmcnt(7)
	v_mfma_f32_16x16x32_bf16 v[68:71], v[164:167], v[36:39], v[68:71]
	ds_read_b128 v[196:199], v133 offset:13120
	v_mul_f32_e32 v230, v54, v230
	v_mul_f32_e32 v231, v55, v231
	s_waitcnt lgkmcnt(7)
; __device__ __forceinline__ bf16x8 packfrag(f32x4 d0, f32x4 d1){ u32x4 t={pack2(d0[0],d0[1]),pack2(d0[2],d0[3]),pack2(d1[0],d1[1]),pack2(d1[2],d1[3])}; return __builtin_bit_cast(bf16x8,t); }
; #define MF(a,b,c) __builtin_amdgcn_mfma_f32_16x16x32_bf16(a,b,c,0,0,0)
; __device__ __forceinline__ void phase_scan(KP kp_){ asm volatile("" : "+s"(kp_)); const Params p=load_params(kp_);
;     ...
;       _Pragma("unroll") for (int q=0;q<4;++q){ int kb=(32*q+kg*4)*2;
;         _Pragma("unroll") for (int t=0;t<4;++t){
;           vn[t]=MF(lds64x2(SWB+(t*16+r)*272+kb), Sf[q], vn[t]);
;           oacc[t]=MF(lds64x2(SQ+(t*16+r)*272+kb), Sf[q], oacc[t]); } }
;       const float* gcs=(const float*)(smem+SGC);
;       float gl = d ? gcs[0] : gcs[63];
;       float gam=__expf(gl);
;       f32x4 vs[4];
;       _Pragma("unroll") for (int t=0;t<4;++t){ float4 g4=*(const float4*)(gcs+t*16+kg*4);
;         oacc[t][0]*=__expf(g4.x); oacc[t][1]*=__expf(g4.y); oacc[t][2]*=__expf(g4.z); oacc[t][3]*=__expf(g4.w);
;         vs[t][0]=vn[t][0]*__expf(gl-g4.x); vs[t][1]=vn[t][1]*__expf(gl-g4.y); vs[t][2]=vn[t][2]*__expf(gl-g4.z); vs[t][3]=vn[t][3]*__expf(gl-g4.w); }
;       bf16x8 Vf[2], Wf[2];
;       _Pragma("unroll") for (int q=0;q<2;++q){ Vf[q]=packfrag(vn[2*q],vn[2*q+1]); Wf[q]=packfrag(vs[2*q],vs[2*q+1]); }
;       _Pragma("unroll") for (int q=0;q<2;++q){ int kb=(32*q+kg*4)*2;
;         _Pragma("unroll") for (int t=0;t<4;++t) oacc[t]=MF(lds64x2(SAT+(t*16+r)*144+kb), Vf[q], oacc[t]); }
;       _Pragma("unroll") for (int m8=0;m8<8;++m8){ Sacc[m8][0]*=gam; Sacc[m8][1]*=gam; Sacc[m8][2]*=gam; Sacc[m8][3]*=gam; }
;       _Pragma("unroll") for (int q=0;q<2;++q){ int kb=(32*q+kg*4)*2;
;         _Pragma("unroll") for (int m8=0;m8<8;++m8) Sacc[m8]=MF(lds64x2(SKT+(m8*16+r)*144+kb), Wf[q], Sacc[m8]); }
	v_mfma_f32_16x16x32_bf16 v[68:71], v[168:171], v[40:43], v[68:71]
	ds_read_b128 v[160:163], v133 offset:13184
	v_cvt_pk_bf16_f32 v90, v52, v53
	v_cvt_pk_bf16_f32 v91, v54, v55
	s_waitcnt lgkmcnt(7)
	v_mfma_f32_16x16x32_bf16 v[68:71], v[172:175], v[44:47], v[68:71]
	ds_read_b128 v[164:167], v133 offset:13248
	v_cvt_pk_bf16_f32 v82, v228, v229
	v_cvt_pk_bf16_f32 v83, v230, v231
	s_waitcnt lgkmcnt(7)
	v_mfma_f32_16x16x32_bf16 v[72:75], v[176:179], v[32:35], 0
	ds_read_b128 v[168:171], v134 offset:35840
	v_mul_f32_e32 v232, v56, v232
	v_mul_f32_e32 v233, v57, v233
	s_waitcnt lgkmcnt(7)
	v_mfma_f32_16x16x32_bf16 v[72:75], v[180:183], v[36:39], v[72:75]
	ds_read_b128 v[172:175], v134 offset:38144
	v_mul_f32_e32 v234, v58, v234
	v_mul_f32_e32 v235, v59, v235
	s_waitcnt lgkmcnt(7)
	v_mfma_f32_16x16x32_bf16 v[72:75], v[184:187], v[40:43], v[72:75]
	ds_read_b128 v[176:179], v134 offset:40448
	v_cvt_pk_bf16_f32 v92, v56, v57
	v_cvt_pk_bf16_f32 v93, v58, v59
	s_waitcnt lgkmcnt(7)
	v_mfma_f32_16x16x32_bf16 v[72:75], v[188:191], v[44:47], v[72:75]
	ds_read_b128 v[180:183], v134 offset:42752
	v_cvt_pk_bf16_f32 v84, v232, v233
	v_cvt_pk_bf16_f32 v85, v234, v235
	s_waitcnt lgkmcnt(7)
	v_mfma_f32_16x16x32_bf16 v[76:79], v[192:195], v[32:35], 0
	ds_read_b128 v[184:187], v134 offset:45056
	v_mul_f32_e32 v236, v60, v236
	v_mul_f32_e32 v237, v61, v237
	s_waitcnt lgkmcnt(7)
	v_mfma_f32_16x16x32_bf16 v[76:79], v[196:199], v[36:39], v[76:79]
	ds_read_b128 v[188:191], v134 offset:47360
	v_mul_f32_e32 v238, v62, v238
	v_mul_f32_e32 v239, v63, v239
	s_waitcnt lgkmcnt(7)
	v_mfma_f32_16x16x32_bf16 v[76:79], v[160:163], v[40:43], v[76:79]
	ds_read_b128 v[192:195], v134 offset:49664
	v_cvt_pk_bf16_f32 v94, v60, v61
	v_cvt_pk_bf16_f32 v95, v62, v63
	s_waitcnt lgkmcnt(7)
	v_mfma_f32_16x16x32_bf16 v[76:79], v[164:167], v[44:47], v[76:79]
	ds_read_b128 v[196:199], v134 offset:51968
	v_cvt_pk_bf16_f32 v86, v236, v237
	v_cvt_pk_bf16_f32 v87, v238, v239
	s_waitcnt lgkmcnt(7)
	v_mfma_f32_16x16x32_bf16 v[0:3], v[168:171], v[80:83], v[0:3]
	ds_read_b128 v[160:163], v134 offset:35904
	ds_read_b128 v[224:227], v137 offset:63488
	s_waitcnt lgkmcnt(8)
	v_mfma_f32_16x16x32_bf16 v[4:7], v[172:175], v[80:83], v[4:7]
	ds_read_b128 v[164:167], v134 offset:38208
	ds_read_b128 v[228:231], v137 offset:63552
	s_waitcnt lgkmcnt(9)
	v_mfma_f32_16x16x32_bf16 v[8:11], v[176:179], v[80:83], v[8:11]
	ds_read_b128 v[168:171], v134 offset:40512
	ds_read_b128 v[232:235], v137 offset:63616
	s_waitcnt lgkmcnt(10)
	v_mfma_f32_16x16x32_bf16 v[12:15], v[180:183], v[80:83], v[12:15]
	ds_read_b128 v[172:175], v134 offset:42816
	ds_read_b128 v[236:239], v137 offset:63680
	s_waitcnt lgkmcnt(11)
	v_mfma_f32_16x16x32_bf16 v[16:19], v[184:187], v[80:83], v[16:19]
	ds_read_b128 v[176:179], v134 offset:45120
	s_waitcnt lgkmcnt(11)
	v_mfma_f32_16x16x32_bf16 v[20:23], v[188:191], v[80:83], v[20:23]
	ds_read_b128 v[180:183], v134 offset:47424
	s_waitcnt lgkmcnt(11)
	v_mfma_f32_16x16x32_bf16 v[24:27], v[192:195], v[80:83], v[24:27]
	ds_read_b128 v[184:187], v134 offset:49728
	s_waitcnt lgkmcnt(11)
	v_mfma_f32_16x16x32_bf16 v[28:31], v[196:199], v[80:83], v[28:31]
	ds_read_b128 v[188:191], v134 offset:52032
	s_waitcnt lgkmcnt(11)
	v_mfma_f32_16x16x32_bf16 v[0:3], v[160:163], v[84:87], v[0:3]
	ds_read_b128 v[192:195], v134 offset:54272
	s_waitcnt lgkmcnt(11)
	v_mul_f32_e32 v64, v64, v224
	v_mul_f32_e32 v65, v65, v225
	s_waitcnt lgkmcnt(10)
	v_mfma_f32_16x16x32_bf16 v[4:7], v[164:167], v[84:87], v[4:7]
	ds_read_b128 v[196:199], v134 offset:56576
	v_mul_f32_e32 v66, v66, v226
	v_mul_f32_e32 v67, v67, v227
	s_waitcnt lgkmcnt(9)
	v_mfma_f32_16x16x32_bf16 v[8:11], v[168:171], v[84:87], v[8:11]
	ds_read_b128 v[160:163], v134 offset:58880
	v_mul_f32_e32 v68, v68, v228
	v_mul_f32_e32 v69, v69, v229
	s_waitcnt lgkmcnt(8)
	v_mfma_f32_16x16x32_bf16 v[12:15], v[172:175], v[84:87], v[12:15]
	ds_read_b128 v[164:167], v134 offset:61184
	v_mul_f32_e32 v70, v70, v230
	v_mul_f32_e32 v71, v71, v231
	s_waitcnt lgkmcnt(7)
	v_mfma_f32_16x16x32_bf16 v[16:19], v[176:179], v[84:87], v[16:19]
	ds_read_b128 v[168:171], v134 offset:54336
	v_mul_f32_e32 v72, v72, v232
	v_mul_f32_e32 v73, v73, v233
	ds_read_b128 v[208:211], v135 offset:17408
	s_waitcnt lgkmcnt(8)
	v_mfma_f32_16x16x32_bf16 v[20:23], v[180:183], v[84:87], v[20:23]
	ds_read_b128 v[172:175], v134 offset:56640
	v_mul_f32_e32 v74, v74, v234
	v_mul_f32_e32 v75, v75, v235
	ds_read_b128 v[212:215], v135 offset:17472
	s_waitcnt lgkmcnt(9)
	v_mfma_f32_16x16x32_bf16 v[24:27], v[184:187], v[84:87], v[24:27]
	ds_read_b128 v[176:179], v134 offset:58944
	v_mul_f32_e32 v76, v76, v236
	v_mul_f32_e32 v77, v77, v237
	ds_read_b128 v[216:219], v203 offset:0
	s_waitcnt lgkmcnt(10)
	v_mfma_f32_16x16x32_bf16 v[28:31], v[188:191], v[84:87], v[28:31]
	ds_read_b128 v[180:183], v134 offset:61248
	v_mul_f32_e32 v78, v78, v238
	v_mul_f32_e32 v79, v79, v239
	ds_read_b128 v[220:223], v203 offset:64
	s_waitcnt lgkmcnt(11)
	v_mfma_f32_16x16x32_bf16 v[64:67], v[192:195], v[88:91], v[64:67]
	ds_read_b128 v[184:187], v202 offset:18432
	s_waitcnt lgkmcnt(11)
	v_mfma_f32_16x16x32_bf16 v[68:71], v[196:199], v[88:91], v[68:71]
	ds_read_b128 v[188:191], v202 offset:20736
	s_waitcnt lgkmcnt(11)
	v_mfma_f32_16x16x32_bf16 v[72:75], v[160:163], v[88:91], v[72:75]
	ds_read_b128 v[192:195], v202 offset:23040
	s_waitcnt lgkmcnt(11)
; __device__ __forceinline__ unsigned pack2(float a, float b){ f32x2_t v={a,b}; bf16x2_t r=__builtin_convertvector(v,bf16x2_t); return __builtin_bit_cast(unsigned,r); }
; #define MF(a,b,c) __builtin_amdgcn_mfma_f32_16x16x32_bf16(a,b,c,0,0,0)
; __device__ __forceinline__ void phase_scan(KP kp_){ asm volatile("" : "+s"(kp_)); const Params p=load_params(kp_);
;     ...
;       _Pragma("unroll") for (int ks=0;ks<2;++ks){ int kb=(ks*32+kg*8)*2;
;         bf16x8 A=lds128(SKT+(wv*16+r)*144+kb);
;         bf16x8 Bv=lds128(SVT+(wv*16+r)*144+kb);
;         _Pragma("unroll") for (int t=0;t<4;++t){
;           wacc[t]=MF(A, lds128(STW+(t*16+r)*144+kb), wacc[t]);
;           vn[t]=MF(lds128(STU+(t*16+r)*144+kb), Bv, vn[t]); } }
;       _Pragma("unroll") for (int t=0;t<4;++t){ uint2 pk2; pk2.x=pack2(-wacc[t][0],-wacc[t][1]); pk2.y=pack2(-wacc[t][2],-wacc[t][3]);
;         *(uint2*)(smem+SWB+(t*16+r)*272+(wv*16+kg*4)*2)=pk2; }
;     ...
;         _Pragma("unroll") for (int m8=0;m8<8;++m8) Sacc[m8]=MF(lds64x2(SKT+(m8*16+r)*144+kb), Wf[q], Sacc[m8]); }
;       if (s>=4){ int cidx=4+(d?131-s:s-4); char* op=tabase+(size_t)((b*8+h)*132+cidx)*TA_STRIDE;
;         _Pragma("unroll") for (int t=0;t<4;++t) _Pragma("unroll") for (int j=0;j<4;++j)
;           *(u16*)(op+((t*16+kg*4+j)*128+wv*16+r)*2)=f2bf(oacc[t][j]); }
;         __syncthreads();
;         if (s+1<132) FILL(A);
;         __syncthreads();
;       }
	v_mfma_f32_16x16x32_bf16 v[76:79], v[164:167], v[88:91], v[76:79]
	ds_read_b128 v[196:199], v202 offset:25344
	s_waitcnt lgkmcnt(11)
	v_mfma_f32_16x16x32_bf16 v[64:67], v[168:171], v[92:95], v[64:67]
	ds_read_b128 v[160:163], v202 offset:18496
	s_waitcnt lgkmcnt(10)
	v_mfma_f32_16x16x32_bf16 v[68:71], v[172:175], v[92:95], v[68:71]
	ds_read_b128 v[164:167], v202 offset:20800
	s_waitcnt lgkmcnt(9)
	v_mfma_f32_16x16x32_bf16 v[72:75], v[176:179], v[92:95], v[72:75]
	ds_read_b128 v[168:171], v202 offset:23104
	s_waitcnt lgkmcnt(8)
	v_mfma_f32_16x16x32_bf16 v[76:79], v[180:183], v[92:95], v[76:79]
	ds_read_b128 v[172:175], v202 offset:25408
	s_waitcnt lgkmcnt(7)
	v_mfma_f32_16x16x32_bf16 v[32:35], v[208:211], v[184:187], 0
	ds_read_b128 v[176:179], v202 offset:27648
	s_waitcnt lgkmcnt(7)
	v_mfma_f32_16x16x32_bf16 v[36:39], v[208:211], v[188:191], 0
	ds_read_b128 v[180:183], v202 offset:29952
	s_waitcnt lgkmcnt(7)
	v_mfma_f32_16x16x32_bf16 v[40:43], v[208:211], v[192:195], 0
	ds_read_b128 v[184:187], v202 offset:32256
	s_waitcnt lgkmcnt(7)
	v_mfma_f32_16x16x32_bf16 v[44:47], v[208:211], v[196:199], 0
	ds_read_b128 v[188:191], v202 offset:34560
	s_waitcnt lgkmcnt(7)
	v_mfma_f32_16x16x32_bf16 v[32:35], v[212:215], v[160:163], v[32:35]
	ds_read_b128 v[192:195], v202 offset:27712
	s_waitcnt lgkmcnt(7)
	v_mfma_f32_16x16x32_bf16 v[36:39], v[212:215], v[164:167], v[36:39]
	ds_read_b128 v[196:199], v202 offset:30016
	s_waitcnt lgkmcnt(7)
	v_mfma_f32_16x16x32_bf16 v[40:43], v[212:215], v[168:171], v[40:43]
	ds_read_b128 v[160:163], v202 offset:32320
	s_waitcnt lgkmcnt(7)
	v_mfma_f32_16x16x32_bf16 v[44:47], v[212:215], v[172:175], v[44:47]
	ds_read_b128 v[164:167], v202 offset:34624
	s_waitcnt lgkmcnt(7)
	v_mfma_f32_16x16x32_bf16 v[48:51], v[176:179], v[216:219], 0
	s_waitcnt lgkmcnt(6)
	v_mfma_f32_16x16x32_bf16 v[52:55], v[180:183], v[216:219], 0
	s_waitcnt vmcnt(0)
	s_add_u32 s12, s10, 1
	s_cmp_lt_u32 s12, 4
	s_cbranch_scc1 .Lmy_sc_nost6
	v_cvt_pk_bf16_f32 v246, v64, v65
	v_cvt_pk_bf16_f32 v247, v66, v67
	global_store_short v156, v246, s[24:25]
	global_store_short_d16_hi v156, v246, s[24:25] offset:256
	global_store_short v156, v247, s[24:25] offset:512
	global_store_short_d16_hi v156, v247, s[24:25] offset:768
	v_cvt_pk_bf16_f32 v248, v68, v69
	v_cvt_pk_bf16_f32 v249, v70, v71
	global_store_short v157, v248, s[24:25]
	global_store_short_d16_hi v157, v248, s[24:25] offset:256
	global_store_short v157, v249, s[24:25] offset:512
	global_store_short_d16_hi v157, v249, s[24:25] offset:768
	s_nop 0
	v_cvt_pk_bf16_f32 v246, v72, v73
	v_cvt_pk_bf16_f32 v247, v74, v75
	global_store_short v158, v246, s[24:25]
	global_store_short_d16_hi v158, v246, s[24:25] offset:256
	global_store_short v158, v247, s[24:25] offset:512
	global_store_short_d16_hi v158, v247, s[24:25] offset:768
	v_cvt_pk_bf16_f32 v248, v76, v77
	v_cvt_pk_bf16_f32 v249, v78, v79
	global_store_short v159, v248, s[24:25]
	global_store_short_d16_hi v159, v248, s[24:25] offset:256
	global_store_short v159, v249, s[24:25] offset:512
	global_store_short_d16_hi v159, v249, s[24:25] offset:768
.Lmy_sc_nost6:
	s_waitcnt lgkmcnt(5)
	v_mfma_f32_16x16x32_bf16 v[56:59], v[184:187], v[216:219], 0
	s_waitcnt lgkmcnt(4)
	v_mfma_f32_16x16x32_bf16 v[60:63], v[188:191], v[216:219], 0
	s_waitcnt lgkmcnt(3)
	v_mfma_f32_16x16x32_bf16 v[48:51], v[192:195], v[220:223], v[48:51]
	v_cvt_pk_bf16_f32 v244, -v32, -v33
	v_cvt_pk_bf16_f32 v245, -v34, -v35
	ds_write_b64 v204, v[244:245] offset:0
	s_waitcnt lgkmcnt(3)
	v_mfma_f32_16x16x32_bf16 v[52:55], v[196:199], v[220:223], v[52:55]
	v_cvt_pk_bf16_f32 v250, -v36, -v37
	v_cvt_pk_bf16_f32 v251, -v38, -v39
	ds_write_b64 v204, v[250:251] offset:4352
	s_waitcnt lgkmcnt(3)
	v_mfma_f32_16x16x32_bf16 v[56:59], v[160:163], v[220:223], v[56:59]
	v_cvt_pk_bf16_f32 v244, -v40, -v41
	v_cvt_pk_bf16_f32 v245, -v42, -v43
	ds_write_b64 v204, v[244:245] offset:8704
	s_waitcnt lgkmcnt(3)
	v_mfma_f32_16x16x32_bf16 v[60:63], v[164:167], v[220:223], v[60:63]
	v_cvt_pk_bf16_f32 v250, -v44, -v45
	v_cvt_pk_bf16_f32 v251, -v46, -v47
	ds_write_b64 v204, v[250:251] offset:13056
	s_waitcnt lgkmcnt(0)
	s_barrier
	ds_write2_b64 v138, v[96:97], v[98:99] offset1:2
	ds_write2_b64 v139, v[100:101], v[102:103] offset1:2
	ds_write2_b64 v145, v[128:129], v[130:131] offset1:2
	s_cmp_lg_u32 s3, 0
	s_cbranch_scc1 .Lmy_sc_noe7
	v_mul_f32_e32 v240, 0x3fb8aa3b, v132
	v_readlane_b32 s12, v132, s11
	s_nop 0
	v_exp_f32_e32 v240, v240
	s_nop 1
	v_sub_f32_e32 v241, s12, v132
	v_mov_b32_e32 v242, s12
	s_nop 0
	v_mul_f32_e32 v241, 0x3fb8aa3b, v241
	v_mul_f32_e32 v242, 0x3fb8aa3b, v242
	s_nop 0
	v_exp_f32_e32 v241, v241
	v_exp_f32_e32 v242, v242
	s_nop 1
	ds_write_b32 v147, v240 offset:63488
	ds_write_b32 v147, v241 offset:63744
	ds_write_b32 v147, v242 offset:64000
.Lmy_sc_noe7:
	ds_write2_b64 v142, v[104:105], v[106:107] offset1:2
	ds_write2_b64 v143, v[108:109], v[110:111] offset1:2
	ds_write_b128 v146, v[112:115] offset:0
	ds_write_b128 v146, v[116:119] offset:9216
	ds_write2_b64 v144, v[120:121], v[122:123] offset1:2
	ds_write_b128 v146, v[124:127] offset:27648
	s_waitcnt lgkmcnt(0)
	s_mov_b64 s[24:25], s[22:23]
	s_mov_b32 s19, s18
	s_mov_b64 s[20:21], s[14:15]
	s_mov_b64 s[22:23], s[16:17]
	s_barrier
	s_add_u32 s10, s10, 2
	s_cmp_lt_u32 s10, 0x84
	s_cbranch_scc1 .Lmy_scan_loop
